# non-temporal hint on the one-shot f32 weight reads of the F1 / F2 conversion tiles
# speedup vs baseline: 1.0059x; 1.0059x over previous
.LBB0_214:
	v_mov_b32_e32 v36, v202
	s_cmp_lt_i32 s30, 0
	s_cbranch_scc1 .LBB0_232
	s_lshl_b64 s[4:5], s[30:31], 2
	v_lshlrev_b32_e32 v0, 2, v36
	s_add_u32 s4, s38, s4
	v_and_b32_e32 v37, 60, v0
	s_addc_u32 s5, s39, s5
	v_lshlrev_b32_e32 v0, 2, v37
	v_lshl_add_u64 v[34:35], s[4:5], 0, v[0:1]
	v_ashrrev_i32_e32 v0, 4, v36
	s_mul_i32 s41, s68, s71
	v_subrev_u32_e32 v2, s41, v0
	v_add_u32_e32 v3, s69, v2
	v_cmp_gt_i32_e32 vcc, s63, v3
	v_mov_b32_e32 v2, 0
	v_mov_b32_e32 v6, 0
	v_mov_b32_e32 v7, 0
	v_mov_b32_e32 v8, 0
	v_mov_b32_e32 v9, 0
	s_and_saveexec_b64 s[14:15], vcc
	s_cbranch_execz .LBB0_217
	v_ashrrev_i32_e32 v4, 31, v3
	v_mul_lo_u32 v6, s57, v3
	v_mul_lo_u32 v7, s56, v4
	v_mad_u64_u32 v[4:5], s[4:5], s56, v3, 0
	v_add3_u32 v5, v5, v7, v6
	v_lshl_add_u64 v[4:5], v[4:5], 2, v[34:35]
	global_load_dwordx4 v[6:9], v[4:5], off nt
.LBB0_217:
	s_or_b64 exec, exec, s[14:15]
	v_add_u32_e32 v3, 0x200, v36
	v_ashrrev_i32_e32 v38, 4, v3
	v_subrev_u32_e32 v3, s41, v38
	v_add_u32_e32 v10, s69, v3
	v_cmp_gt_i32_e32 vcc, s63, v10
	v_mov_b32_e32 v3, 0
	v_mov_b32_e32 v4, 0
	v_mov_b32_e32 v5, 0
	s_and_saveexec_b64 s[14:15], vcc
	s_cbranch_execz .LBB0_219
	v_ashrrev_i32_e32 v2, 31, v10
	v_mul_lo_u32 v4, s57, v10
	v_mul_lo_u32 v5, s56, v2
	v_mad_u64_u32 v[2:3], s[4:5], s56, v10, 0
	v_add3_u32 v3, v3, v5, v4
	v_lshl_add_u64 v[2:3], v[2:3], 2, v[34:35]
	global_load_dwordx4 v[2:5], v[2:3], off nt
.LBB0_219:
	s_or_b64 exec, exec, s[14:15]
	v_add_u32_e32 v10, 0x400, v36
	v_ashrrev_i32_e32 v39, 4, v10
	v_subrev_u32_e32 v10, s41, v39
	v_add_u32_e32 v11, s69, v10
	v_cmp_gt_i32_e32 vcc, s63, v11
	v_mov_b32_e32 v10, 0
	v_mov_b32_e32 v14, 0
	v_mov_b32_e32 v15, 0
	v_mov_b32_e32 v16, 0
	v_mov_b32_e32 v17, 0
	s_and_saveexec_b64 s[14:15], vcc
	s_cbranch_execz .LBB0_221
	v_ashrrev_i32_e32 v12, 31, v11
	v_mul_lo_u32 v14, s57, v11
	v_mul_lo_u32 v15, s56, v12
	v_mad_u64_u32 v[12:13], s[4:5], s56, v11, 0
	v_add3_u32 v13, v13, v15, v14
	v_lshl_add_u64 v[12:13], v[12:13], 2, v[34:35]
	global_load_dwordx4 v[14:17], v[12:13], off nt
.LBB0_221:
	s_or_b64 exec, exec, s[14:15]
	v_add_u32_e32 v11, 0x600, v36
	v_ashrrev_i32_e32 v40, 4, v11
	v_subrev_u32_e32 v11, s41, v40
	v_add_u32_e32 v18, s69, v11
	v_cmp_gt_i32_e32 vcc, s63, v18
	v_mov_b32_e32 v11, 0
	v_mov_b32_e32 v12, 0
	v_mov_b32_e32 v13, 0
	s_and_saveexec_b64 s[14:15], vcc
	s_cbranch_execz .LBB0_223
	v_ashrrev_i32_e32 v10, 31, v18
	v_mul_lo_u32 v12, s57, v18
	v_mul_lo_u32 v13, s56, v10
	v_mad_u64_u32 v[10:11], s[4:5], s56, v18, 0
	v_add3_u32 v11, v11, v13, v12
	v_lshl_add_u64 v[10:11], v[10:11], 2, v[34:35]
	global_load_dwordx4 v[10:13], v[10:11], off nt
.LBB0_223:
	s_or_b64 exec, exec, s[14:15]
	v_add_u32_e32 v18, 0x800, v36
	v_ashrrev_i32_e32 v41, 4, v18
	v_subrev_u32_e32 v18, s41, v41
	v_add_u32_e32 v19, s69, v18
	v_cmp_gt_i32_e32 vcc, s63, v19
	v_mov_b32_e32 v18, 0
	v_mov_b32_e32 v22, 0
	v_mov_b32_e32 v23, 0
	v_mov_b32_e32 v24, 0
	v_mov_b32_e32 v25, 0
	s_and_saveexec_b64 s[14:15], vcc
	s_cbranch_execz .LBB0_225
	v_ashrrev_i32_e32 v20, 31, v19
	v_mul_lo_u32 v22, s57, v19
	v_mul_lo_u32 v23, s56, v20
	v_mad_u64_u32 v[20:21], s[4:5], s56, v19, 0
	v_add3_u32 v21, v21, v23, v22
	v_lshl_add_u64 v[20:21], v[20:21], 2, v[34:35]
	global_load_dwordx4 v[22:25], v[20:21], off nt
.LBB0_225:
	s_or_b64 exec, exec, s[14:15]
	v_add_u32_e32 v19, 0xa00, v36
	v_ashrrev_i32_e32 v42, 4, v19
	v_subrev_u32_e32 v19, s41, v42
	v_add_u32_e32 v26, s69, v19
	v_cmp_gt_i32_e32 vcc, s63, v26
	v_mov_b32_e32 v19, 0
	v_mov_b32_e32 v20, 0
	v_mov_b32_e32 v21, 0
	s_and_saveexec_b64 s[14:15], vcc
	s_cbranch_execz .LBB0_227
	v_ashrrev_i32_e32 v18, 31, v26
	v_mul_lo_u32 v20, s57, v26
	v_mul_lo_u32 v21, s56, v18
	v_mad_u64_u32 v[18:19], s[4:5], s56, v26, 0
	v_add3_u32 v19, v19, v21, v20
	v_lshl_add_u64 v[18:19], v[18:19], 2, v[34:35]
	global_load_dwordx4 v[18:21], v[18:19], off nt
.LBB0_227:
	s_or_b64 exec, exec, s[14:15]
	v_add_u32_e32 v26, 0xc00, v36
	v_ashrrev_i32_e32 v43, 4, v26
	v_subrev_u32_e32 v26, s41, v43
	v_add_u32_e32 v27, s69, v26
	v_cmp_gt_i32_e32 vcc, s63, v27
	v_mov_b32_e32 v26, 0
	v_mov_b32_e32 v30, 0
	v_mov_b32_e32 v31, 0
	v_mov_b32_e32 v32, 0
	v_mov_b32_e32 v33, 0
	s_and_saveexec_b64 s[14:15], vcc
	s_cbranch_execz .LBB0_229
	v_ashrrev_i32_e32 v28, 31, v27
	v_mul_lo_u32 v30, s57, v27
	v_mul_lo_u32 v31, s56, v28
	v_mad_u64_u32 v[28:29], s[4:5], s56, v27, 0
	v_add3_u32 v29, v29, v31, v30
	v_lshl_add_u64 v[28:29], v[28:29], 2, v[34:35]
	global_load_dwordx4 v[30:33], v[28:29], off nt
.LBB0_229:
	s_or_b64 exec, exec, s[14:15]
	v_add_u32_e32 v27, 0xe00, v36
	v_ashrrev_i32_e32 v44, 4, v27
	v_subrev_u32_e32 v27, s41, v44
	v_add_u32_e32 v45, s69, v27
	v_cmp_gt_i32_e32 vcc, s63, v45
	v_mov_b32_e32 v27, 0
	v_mov_b32_e32 v28, 0
	v_mov_b32_e32 v29, 0
	s_and_saveexec_b64 s[14:15], vcc
	s_cbranch_execz .LBB0_231
	v_ashrrev_i32_e32 v26, 31, v45
	v_mul_lo_u32 v28, s57, v45
	v_mul_lo_u32 v29, s56, v26
	v_mad_u64_u32 v[26:27], s[4:5], s56, v45, 0
	v_add3_u32 v27, v27, v29, v28
	v_lshl_add_u64 v[26:27], v[26:27], 2, v[34:35]
	global_load_dwordx4 v[26:29], v[26:27], off nt

.LBB0_925:
	s_mul_hi_i32 s10, s19, 0x2e8ba2e9
	s_lshr_b32 s11, s10, 31
	s_ashr_i32 s20, s10, 1
	s_add_i32 s20, s20, s11
	s_lshl_b32 s30, s20, 6
	v_mov_b32_e32 v38, v202
	s_cmp_lt_i32 s19, -10
	s_cbranch_scc1 .LBB0_943
	s_lshl_b64 s[10:11], s[30:31], 2
	v_lshlrev_b32_e32 v0, 2, v38
	s_add_u32 s10, s16, s10
	v_and_b32_e32 v39, 60, v0
	s_addc_u32 s11, s17, s11
	v_lshlrev_b32_e32 v0, 2, v39
	v_lshl_add_u64 v[34:35], s[10:11], 0, v[0:1]
	v_ashrrev_i32_e32 v0, 4, v38
	s_mul_i32 s14, s20, 0xb00
	v_subrev_u32_e32 v2, s14, v0
	v_add_u32_e32 v4, s18, v2
	v_cmp_gt_i32_e32 vcc, s42, v4
	v_mov_b32_e32 v2, 0
	v_mov_b32_e32 v6, 0
	v_mov_b32_e32 v7, 0
	v_mov_b32_e32 v8, 0
	v_mov_b32_e32 v9, 0
	s_and_saveexec_b64 s[10:11], vcc
	s_cbranch_execz .LBB0_928
	v_ashrrev_i32_e32 v5, 31, v4
	v_lshlrev_b64 v[4:5], 12, v[4:5]
	v_lshl_add_u64 v[4:5], v[34:35], 0, v[4:5]
	global_load_dwordx4 v[6:9], v[4:5], off nt
.LBB0_928:
	s_or_b64 exec, exec, s[10:11]
	v_add_u32_e32 v3, 0x200, v38
	v_ashrrev_i32_e32 v40, 4, v3
	v_subrev_u32_e32 v3, s14, v40
	v_add_u32_e32 v10, s18, v3
	v_cmp_gt_i32_e32 vcc, s42, v10
	v_mov_b32_e32 v3, 0
	v_mov_b32_e32 v4, 0
	v_mov_b32_e32 v5, 0
	s_and_saveexec_b64 s[10:11], vcc
	s_cbranch_execz .LBB0_930
	v_ashrrev_i32_e32 v11, 31, v10
	v_lshlrev_b64 v[2:3], 12, v[10:11]
	v_lshl_add_u64 v[2:3], v[34:35], 0, v[2:3]
	global_load_dwordx4 v[2:5], v[2:3], off nt
.LBB0_930:
	s_or_b64 exec, exec, s[10:11]
	v_add_u32_e32 v10, 0x400, v38
	v_ashrrev_i32_e32 v41, 4, v10
	v_subrev_u32_e32 v10, s14, v41
	v_add_u32_e32 v12, s18, v10
	v_cmp_gt_i32_e32 vcc, s42, v12
	v_mov_b32_e32 v10, 0
	v_mov_b32_e32 v14, 0
	v_mov_b32_e32 v15, 0
	v_mov_b32_e32 v16, 0
	v_mov_b32_e32 v17, 0
	s_and_saveexec_b64 s[10:11], vcc
	s_cbranch_execz .LBB0_932
	v_ashrrev_i32_e32 v13, 31, v12
	v_lshlrev_b64 v[12:13], 12, v[12:13]
	v_lshl_add_u64 v[12:13], v[34:35], 0, v[12:13]
	global_load_dwordx4 v[14:17], v[12:13], off nt
.LBB0_932:
	s_or_b64 exec, exec, s[10:11]
	v_add_u32_e32 v11, 0x600, v38
	v_ashrrev_i32_e32 v42, 4, v11
	v_subrev_u32_e32 v11, s14, v42
	v_add_u32_e32 v18, s18, v11
	v_cmp_gt_i32_e32 vcc, s42, v18
	v_mov_b32_e32 v11, 0
	v_mov_b32_e32 v12, 0
	v_mov_b32_e32 v13, 0
	s_and_saveexec_b64 s[10:11], vcc
	s_cbranch_execz .LBB0_934
	v_ashrrev_i32_e32 v19, 31, v18
	v_lshlrev_b64 v[10:11], 12, v[18:19]
	v_lshl_add_u64 v[10:11], v[34:35], 0, v[10:11]
	global_load_dwordx4 v[10:13], v[10:11], off nt
.LBB0_934:
	s_or_b64 exec, exec, s[10:11]
	v_add_u32_e32 v18, 0x800, v38
	v_ashrrev_i32_e32 v43, 4, v18
	v_subrev_u32_e32 v18, s14, v43
	v_add_u32_e32 v20, s18, v18
	v_cmp_gt_i32_e32 vcc, s42, v20
	v_mov_b32_e32 v18, 0
	v_mov_b32_e32 v22, 0
	v_mov_b32_e32 v23, 0
	v_mov_b32_e32 v24, 0
	v_mov_b32_e32 v25, 0
	s_and_saveexec_b64 s[10:11], vcc
	s_cbranch_execz .LBB0_936
	v_ashrrev_i32_e32 v21, 31, v20
	v_lshlrev_b64 v[20:21], 12, v[20:21]
	v_lshl_add_u64 v[20:21], v[34:35], 0, v[20:21]
	global_load_dwordx4 v[22:25], v[20:21], off nt
.LBB0_936:
	s_or_b64 exec, exec, s[10:11]
	v_add_u32_e32 v19, 0xa00, v38
	v_ashrrev_i32_e32 v44, 4, v19
	v_subrev_u32_e32 v19, s14, v44
	v_add_u32_e32 v26, s18, v19
	v_cmp_gt_i32_e32 vcc, s42, v26
	v_mov_b32_e32 v19, 0
	v_mov_b32_e32 v20, 0
	v_mov_b32_e32 v21, 0
	s_and_saveexec_b64 s[10:11], vcc
	s_cbranch_execz .LBB0_938
	v_ashrrev_i32_e32 v27, 31, v26
	v_lshlrev_b64 v[18:19], 12, v[26:27]
	v_lshl_add_u64 v[18:19], v[34:35], 0, v[18:19]
	global_load_dwordx4 v[18:21], v[18:19], off nt
.LBB0_938:
	s_or_b64 exec, exec, s[10:11]
	v_add_u32_e32 v26, 0xc00, v38
	v_ashrrev_i32_e32 v45, 4, v26
	v_subrev_u32_e32 v26, s14, v45
	v_add_u32_e32 v28, s18, v26
	v_cmp_gt_i32_e32 vcc, s42, v28
	v_mov_b32_e32 v26, 0
	v_mov_b32_e32 v30, 0
	v_mov_b32_e32 v31, 0
	v_mov_b32_e32 v32, 0
	v_mov_b32_e32 v33, 0
	s_and_saveexec_b64 s[10:11], vcc
	s_cbranch_execz .LBB0_940
	v_ashrrev_i32_e32 v29, 31, v28
	v_lshlrev_b64 v[28:29], 12, v[28:29]
	v_lshl_add_u64 v[28:29], v[34:35], 0, v[28:29]
	global_load_dwordx4 v[30:33], v[28:29], off nt
.LBB0_940:
	s_or_b64 exec, exec, s[10:11]
	v_add_u32_e32 v27, 0xe00, v38
	v_ashrrev_i32_e32 v46, 4, v27
	v_subrev_u32_e32 v27, s14, v46
	v_add_u32_e32 v36, s18, v27
	v_cmp_gt_i32_e32 vcc, s42, v36
	v_mov_b32_e32 v27, 0
	v_mov_b32_e32 v28, 0
	v_mov_b32_e32 v29, 0
	s_and_saveexec_b64 s[10:11], vcc
	s_cbranch_execz .LBB0_942
	v_ashrrev_i32_e32 v37, 31, v36
	v_lshlrev_b64 v[26:27], 12, v[36:37]
	v_lshl_add_u64 v[26:27], v[34:35], 0, v[26:27]
	global_load_dwordx4 v[26:29], v[26:27], off nt
